# placement pad +16 bytes after fox prologue
# baseline (speedup 1.0000x reference)
; #define GAS __attribute__((address_space(1)))
; template <int MODE> ...
;     ...
;     u32x4 kreg = *(const GAS u32x4*)(kg + (size_t)t_first * 64 * LDH), vreg = *(const GAS u32x4*)(vg + (size_t)t_first * 64 * LDH);
;     float cq = 0.f;
;     if (MODE == 0) {
;         float lf[4];
; #pragma unroll
;         for (int i = 0; i < 4; ++i) { const float x = FL[(rowbase + 4 * tid + i) * 8] + bfv; lf[i] = (fminf(x, 0.f) - __logf(1.f + __expf(-fabsf(x)))) * L2E; }
;         const float s1 = lf[0], s2 = s1 + lf[1], s3 = s2 + lf[2], s4 = s3 + lf[3];
;         float v = s4;
; #pragma unroll
;         for (int off = 1; off < 64; off <<= 1) { const float n = __shfl_up(v, off); if (lane >= off) v += n; }
;         if (lane == 63) wt[wid] = v;
;         __syncthreads();
.LBB0_811:
	v_readlane_b32 s2, v254, 8
	s_mul_i32 s0, s2, 0x2aab
	s_lshr_b32 s1, s0, 31
	s_lshr_b32 s0, s0, 16
	s_add_i32 s0, s0, s1
	s_mul_i32 s1, s0, 6
	s_sub_i32 s4, s2, s1
	s_sext_i32_i16 s1, s4
	s_bfe_i64 s[4:5], s[4:5], 0x100000
	s_lshl_b32 s2, s1, 6
	s_lshl_b64 s[4:5], s[4:5], 2
	v_readlane_b32 s1, v252, 58
	s_add_u32 s8, s1, s4
	v_readlane_b32 s1, v252, 59
	s_addc_u32 s9, s1, s5
	s_add_u32 s4, s23, s4
	v_readlane_b32 s1, v252, 55
	s_addc_u32 s5, s1, s5
	v_mov_b32_e32 v1, v230
	global_load_dword v19, v0, s[4:5]
	s_ashr_i32 s3, s2, 31
	v_readfirstlane_b32 s1, v1
	s_ashr_i32 s6, s1, 6
	s_bfe_i64 s[0:1], s[0:1], 0x100000
	s_lshl_b64 s[4:5], s[0:1], 11
	v_readlane_b32 s0, v252, 56
	v_ashrrev_i32_e32 v18, 3, v1
	v_readlane_b32 s1, v252, 57
	v_add_u32_e32 v4, s4, v18
	v_lshlrev_b32_e32 v12, 2, v1
	v_mov_b64_e32 v[2:3], s[0:1]
	s_movk_i32 s0, 0x1880
	v_mad_i64_i32 v[2:3], s[0:1], v4, s0, v[2:3]
	v_lshlrev_b32_e32 v4, 3, v1
	v_ashrrev_i32_e32 v13, 31, v12
	v_and_b32_e32 v4, 56, v4
	v_lshl_add_u64 v[14:15], s[4:5], 0, v[12:13]
	v_lshl_add_u64 v[2:3], s[2:3], 1, v[2:3]
	v_lshlrev_b32_e32 v10, 1, v4
	v_mov_b32_e32 v11, v0
	v_lshlrev_b64 v[14:15], 5, v[14:15]
	v_lshl_add_u64 v[98:99], v[2:3], 0, v[10:11]
	v_lshl_add_u64 v[16:17], s[8:9], 0, v[14:15]
	global_load_dwordx4 v[2:5], v[98:99], off offset:768
	global_load_dwordx4 v[6:9], v[98:99], off offset:1536
	global_load_dword v11, v[16:17], off
	global_load_dword v176, v[16:17], off offset:32
	global_load_dword v177, v[16:17], off offset:64
	global_load_dword v179, v[16:17], off offset:96
	s_mov_b32 s8, 0xbfb8aa3b
	s_mov_b32 s7, 0x800000
	s_mov_b32 s9, 0x3f317217
	s_mov_b32 s10, 0x7f800000
	v_mov_b32_e32 v21, 0x41b17218
	s_waitcnt vmcnt(0)
	v_add_f32_e32 v11, v19, v11
	v_min_f32_e32 v13, 0, v11
	v_mul_f32_e64 v11, |v11|, s8
	v_exp_f32_e32 v11, v11
	s_nop 0
	v_add_f32_e32 v11, 1.0, v11
	v_cmp_gt_f32_e32 vcc, s7, v11
	s_nop 1
	v_cndmask_b32_e64 v14, 0, 32, vcc
	v_ldexp_f32 v11, v11, v14
	v_log_f32_e32 v11, v11
	s_nop 0
	v_mul_f32_e32 v14, 0x3f317217, v11
	v_fma_f32 v14, v11, s9, -v14
	v_fmac_f32_e32 v14, 0x3377d1cf, v11
	v_fmac_f32_e32 v14, 0x3f317217, v11
	v_cmp_lt_f32_e64 s[0:1], |v11|, s10
	s_nop 1
	v_cndmask_b32_e64 v11, v11, v14, s[0:1]
	v_cndmask_b32_e32 v14, 0, v21, vcc
	v_sub_f32_e32 v11, v11, v14
	v_sub_f32_e32 v11, v13, v11
	v_mul_f32_e32 v14, 0x3fb8aa3b, v11
	v_add_f32_e32 v11, v19, v176
	v_min_f32_e32 v13, 0, v11
	v_mul_f32_e64 v11, |v11|, s8
	v_exp_f32_e32 v11, v11
	s_nop 0
	v_add_f32_e32 v11, 1.0, v11
	v_cmp_gt_f32_e32 vcc, s7, v11
	s_nop 1
	v_cndmask_b32_e64 v15, 0, 32, vcc
	v_ldexp_f32 v11, v11, v15
	v_log_f32_e32 v11, v11
	s_nop 0
	v_mul_f32_e32 v15, 0x3f317217, v11
	v_fma_f32 v15, v11, s9, -v15
	v_fmac_f32_e32 v15, 0x3377d1cf, v11
	v_fmac_f32_e32 v15, 0x3f317217, v11
	v_cmp_lt_f32_e64 s[0:1], |v11|, s10
	s_nop 1
	v_cndmask_b32_e64 v11, v11, v15, s[0:1]
	v_cndmask_b32_e32 v15, 0, v21, vcc
	v_sub_f32_e32 v11, v11, v15
	v_sub_f32_e32 v13, v13, v11
	v_add_f32_e32 v11, v19, v177
	v_min_f32_e32 v15, 0, v11
	v_mul_f32_e64 v11, |v11|, s8
	v_exp_f32_e32 v11, v11
	s_nop 0
	v_add_f32_e32 v11, 1.0, v11
	v_cmp_gt_f32_e32 vcc, s7, v11
	s_nop 1
	v_cndmask_b32_e64 v20, 0, 32, vcc
	v_ldexp_f32 v11, v11, v20
	v_log_f32_e32 v11, v11
	s_nop 0
	v_mul_f32_e32 v20, 0x3f317217, v11
	v_fma_f32 v20, v11, s9, -v20
	v_fmac_f32_e32 v20, 0x3377d1cf, v11
	v_fmac_f32_e32 v20, 0x3f317217, v11
	v_cmp_lt_f32_e64 s[0:1], |v11|, s10
	s_nop 1
	v_cndmask_b32_e64 v11, v11, v20, s[0:1]
	v_cndmask_b32_e32 v20, 0, v21, vcc
	v_sub_f32_e32 v11, v11, v20
	v_sub_f32_e32 v20, v15, v11
	v_add_f32_e32 v11, v19, v179
	s_nop 0
	s_nop 0
	s_nop 0
	s_nop 0
	s_nop 0
	s_nop 0
	s_nop 0
	v_min_f32_e32 v15, 0, v11
	v_mul_f32_e64 v11, |v11|, s8
	v_exp_f32_e32 v11, v11
	v_add_u32_e32 v19, -1, v224
	v_add_f32_e32 v11, 1.0, v11
	v_cmp_gt_f32_e32 vcc, s7, v11
	s_nop 1
	v_cndmask_b32_e64 v16, 0, 32, vcc
	v_ldexp_f32 v11, v11, v16
	v_log_f32_e32 v11, v11
	s_nop 0
	v_mul_f32_e32 v16, 0x3f317217, v11
	v_fma_f32 v16, v11, s9, -v16
	v_fmac_f32_e32 v16, 0x3377d1cf, v11
	v_fmac_f32_e32 v16, 0x3f317217, v11
	v_cmp_lt_f32_e64 s[0:1], |v11|, s10
	s_nop 1
	v_cndmask_b32_e64 v11, v11, v16, s[0:1]
	v_cndmask_b32_e32 v16, 0, v21, vcc
	v_sub_f32_e32 v11, v11, v16
	v_sub_f32_e32 v17, v15, v11
	v_fmamk_f32 v15, v13, 0x3fb8aa3b, v14
	v_and_b32_e32 v13, 64, v224
	v_cmp_lt_i32_e32 vcc, v19, v13
	v_fmamk_f32 v16, v20, 0x3fb8aa3b, v15
	v_fmamk_f32 v17, v17, 0x3fb8aa3b, v16
	v_cndmask_b32_e32 v19, v19, v224, vcc
	v_lshlrev_b32_e32 v19, 2, v19
	ds_bpermute_b32 v19, v19, v17
	v_and_b32_e32 v11, 63, v1
	v_cmp_eq_u32_e32 vcc, 0, v11
	v_add_u32_e32 v20, -2, v224
	s_waitcnt lgkmcnt(0)
	v_add_f32_e32 v19, v17, v19
	v_cndmask_b32_e32 v19, v19, v17, vcc
	v_cmp_lt_i32_e32 vcc, v20, v13
	s_nop 1
	v_cndmask_b32_e32 v20, v20, v224, vcc
	v_lshlrev_b32_e32 v20, 2, v20
	ds_bpermute_b32 v20, v20, v19
	v_cmp_gt_u32_e32 vcc, 2, v11
	s_waitcnt lgkmcnt(0)
	v_add_f32_e32 v20, v19, v20
	v_cndmask_b32_e32 v19, v20, v19, vcc
	v_add_u32_e32 v20, -4, v224
	v_cmp_lt_i32_e32 vcc, v20, v13
	s_nop 1
	v_cndmask_b32_e32 v20, v20, v224, vcc
	v_lshlrev_b32_e32 v20, 2, v20
	ds_bpermute_b32 v20, v20, v19
	v_cmp_gt_u32_e32 vcc, 4, v11
	s_waitcnt lgkmcnt(0)
	v_add_f32_e32 v20, v19, v20
	v_cndmask_b32_e32 v19, v20, v19, vcc
	v_add_u32_e32 v20, -8, v224
	v_cmp_lt_i32_e32 vcc, v20, v13
	s_nop 1
	v_cndmask_b32_e32 v20, v20, v224, vcc
	v_lshlrev_b32_e32 v20, 2, v20
	ds_bpermute_b32 v20, v20, v19
	v_cmp_gt_u32_e32 vcc, 8, v11
	s_waitcnt lgkmcnt(0)
	v_add_f32_e32 v20, v19, v20
	v_cndmask_b32_e32 v19, v20, v19, vcc
	v_add_u32_e32 v20, -16, v224
	v_cmp_lt_i32_e32 vcc, v20, v13
	s_nop 1
	v_cndmask_b32_e32 v20, v20, v224, vcc
	v_lshlrev_b32_e32 v20, 2, v20
	ds_bpermute_b32 v20, v20, v19
	v_cmp_gt_u32_e32 vcc, 16, v11
	s_waitcnt lgkmcnt(0)
	v_add_f32_e32 v20, v19, v20
	v_cndmask_b32_e32 v19, v20, v19, vcc
	v_subrev_u32_e32 v20, 32, v224
	v_cmp_lt_i32_e32 vcc, v20, v13
	s_nop 1
	v_cndmask_b32_e32 v20, v20, v224, vcc
	v_lshlrev_b32_e32 v20, 2, v20
	ds_bpermute_b32 v20, v20, v19
	v_cmp_eq_u32_e32 vcc, 63, v11
	s_waitcnt lgkmcnt(0)
	v_add_f32_e32 v20, v19, v20
	s_and_saveexec_b64 s[0:1], vcc
	s_lshl_b32 s7, s6, 2
	s_add_i32 s7, s7, 0
	v_mov_b32_e32 v21, s7
	ds_write_b32 v21, v20 offset:45056
	s_or_b64 exec, exec, s[0:1]
	s_cmp_lt_i32 s6, 1
	s_waitcnt lgkmcnt(0)
	s_barrier
	s_cbranch_scc1 .LBB0_860
	ds_read_b32 v21, v0 offset:45056
	s_waitcnt lgkmcnt(0)
	v_add_f32_e32 v21, 0, v21
	s_cmp_lt_i32 s6, 2
	s_cbranch_scc1 .LBB0_816
